# all accumulated edits: + S5 scan from registers, EpiS2 load pipelining, row-pass sample-row hoisting, QKV/GLU K-split sample GEMMs
# speedup vs baseline: 1.0093x; 1.0088x over previous
; __global__ void __launch_bounds__(512, 2) mega(Params p) {
;     ...
;           float c_r = 1.f, c_i = 0.f, hr = 0.f, hi = 0.f;
;           const float* Sp = Sbuf + ((size_t)g * 2048 + b * 512 + wave * 64) * 128 + lane; bf16_t* Hp = Ap + ((size_t)g * 2048 + b * 512 + wave * 64) * 384 + lane;
;           if (act) {
;             const float dt = __expf(p.in[12][g]); const float zr = p.in[10][g * 64 + lane] * dt * 16.f, zi = p.in[11][g * 64 + lane] * dt * 16.f;
;             float sn, cs; sincos_acc(zi, sn, cs); const float mag = __expf(zr); c_r = mag * cs; c_i = mag * sn;
;             for (int c0 = 0; c0 < 64; c0 += 16) { float sr[16], si[16];
; #pragma unroll
;                 for (int k = 0; k < 16; ++k) { sr[k] = Sp[(size_t)(c0 + k) * 128]; si[k] = Sp[(size_t)(c0 + k) * 128 + 64]; }
; #pragma unroll
;                 for (int k = 0; k < 16; ++k) { const float n_r = c_r * hr - c_i * hi + sr[k], n_i = c_r * hi + c_i * hr + si[k]; hr = n_r; hi = n_i; } }
.LBB0_670:
	v_add_co_u32_e32 v200, vcc, 0xffffe100, v4
	s_nop 1
	v_addc_co_u32_e32 v201, vcc, -1, v5, vcc
	v_add_co_u32_e32 v202, vcc, 0x1000, v200
	s_nop 1
	v_addc_co_u32_e32 v203, vcc, 0, v201, vcc
	v_add_co_u32_e32 v204, vcc, 0x2000, v200
	s_nop 1
	v_addc_co_u32_e32 v205, vcc, 0, v201, vcc
	v_add_co_u32_e32 v206, vcc, 0x3000, v200
	s_nop 1
	v_addc_co_u32_e32 v207, vcc, 0, v201, vcc
	v_add_co_u32_e32 v208, vcc, 0x4000, v200
	s_nop 1
	v_addc_co_u32_e32 v209, vcc, 0, v201, vcc
	v_add_co_u32_e32 v210, vcc, 0x5000, v200
	s_nop 1
	v_addc_co_u32_e32 v211, vcc, 0, v201, vcc
	v_add_co_u32_e32 v212, vcc, 0x6000, v200
	s_nop 1
	v_addc_co_u32_e32 v213, vcc, 0, v201, vcc
	v_add_co_u32_e32 v214, vcc, 0x7000, v200
	s_nop 1
	v_addc_co_u32_e32 v215, vcc, 0, v201, vcc
	global_load_dword v54, v[200:201], off
	global_load_dword v55, v[200:201], off offset:256
	global_load_dword v56, v[200:201], off offset:512
	global_load_dword v57, v[200:201], off offset:768
	global_load_dword v58, v[200:201], off offset:1024
	global_load_dword v59, v[200:201], off offset:1280
	global_load_dword v60, v[200:201], off offset:1536
	global_load_dword v61, v[200:201], off offset:1792
	global_load_dword v62, v[200:201], off offset:2048
	global_load_dword v63, v[200:201], off offset:2304
	global_load_dword v64, v[200:201], off offset:2560
	global_load_dword v65, v[200:201], off offset:2816
	global_load_dword v66, v[200:201], off offset:3072
	global_load_dword v67, v[200:201], off offset:3328
	global_load_dword v68, v[200:201], off offset:3584
	global_load_dword v69, v[200:201], off offset:3840
	global_load_dword v70, v[202:203], off
	global_load_dword v71, v[202:203], off offset:256
	global_load_dword v72, v[202:203], off offset:512
	global_load_dword v73, v[202:203], off offset:768
	global_load_dword v74, v[202:203], off offset:1024
	global_load_dword v75, v[202:203], off offset:1280
	global_load_dword v76, v[202:203], off offset:1536
	global_load_dword v77, v[202:203], off offset:1792
	global_load_dword v78, v[202:203], off offset:2048
	global_load_dword v79, v[202:203], off offset:2304
	global_load_dword v80, v[202:203], off offset:2560
	global_load_dword v81, v[202:203], off offset:2816
	global_load_dword v82, v[202:203], off offset:3072
	global_load_dword v83, v[202:203], off offset:3328
	global_load_dword v84, v[202:203], off offset:3584
	global_load_dword v85, v[202:203], off offset:3840
	global_load_dword v86, v[204:205], off
	global_load_dword v87, v[204:205], off offset:256
	global_load_dword v88, v[204:205], off offset:512
	global_load_dword v89, v[204:205], off offset:768
	global_load_dword v90, v[204:205], off offset:1024
	global_load_dword v91, v[204:205], off offset:1280
	global_load_dword v92, v[204:205], off offset:1536
	global_load_dword v93, v[204:205], off offset:1792
	global_load_dword v94, v[204:205], off offset:2048
	global_load_dword v95, v[204:205], off offset:2304
	global_load_dword v96, v[204:205], off offset:2560
	global_load_dword v97, v[204:205], off offset:2816
	global_load_dword v98, v[204:205], off offset:3072
	global_load_dword v99, v[204:205], off offset:3328
	global_load_dword v100, v[204:205], off offset:3584
	global_load_dword v101, v[204:205], off offset:3840
	global_load_dword v102, v[206:207], off
	global_load_dword v103, v[206:207], off offset:256
	global_load_dword v104, v[206:207], off offset:512
	global_load_dword v105, v[206:207], off offset:768
	global_load_dword v106, v[206:207], off offset:1024
	global_load_dword v107, v[206:207], off offset:1280
	global_load_dword v108, v[206:207], off offset:1536
	global_load_dword v109, v[206:207], off offset:1792
	global_load_dword v110, v[206:207], off offset:2048
	global_load_dword v111, v[206:207], off offset:2304
	global_load_dword v112, v[206:207], off offset:2560
	global_load_dword v113, v[206:207], off offset:2816
	global_load_dword v114, v[206:207], off offset:3072
	global_load_dword v115, v[206:207], off offset:3328
	global_load_dword v116, v[206:207], off offset:3584
	global_load_dword v117, v[206:207], off offset:3840
	global_load_dword v118, v[208:209], off
	global_load_dword v119, v[208:209], off offset:256
	global_load_dword v120, v[208:209], off offset:512
	global_load_dword v121, v[208:209], off offset:768
	global_load_dword v122, v[208:209], off offset:1024
	global_load_dword v123, v[208:209], off offset:1280
	global_load_dword v124, v[208:209], off offset:1536
	global_load_dword v125, v[208:209], off offset:1792
	global_load_dword v130, v[208:209], off offset:2048
	global_load_dword v131, v[208:209], off offset:2304
	global_load_dword v132, v[208:209], off offset:2560
	global_load_dword v133, v[208:209], off offset:2816
	global_load_dword v134, v[208:209], off offset:3072
	global_load_dword v135, v[208:209], off offset:3328
	global_load_dword v136, v[208:209], off offset:3584
	global_load_dword v137, v[208:209], off offset:3840
	global_load_dword v138, v[210:211], off
	global_load_dword v139, v[210:211], off offset:256
	global_load_dword v140, v[210:211], off offset:512
	global_load_dword v141, v[210:211], off offset:768
	global_load_dword v142, v[210:211], off offset:1024
	global_load_dword v143, v[210:211], off offset:1280
	global_load_dword v144, v[210:211], off offset:1536
	global_load_dword v145, v[210:211], off offset:1792
	global_load_dword v146, v[210:211], off offset:2048
	global_load_dword v147, v[210:211], off offset:2304
	global_load_dword v148, v[210:211], off offset:2560
	global_load_dword v149, v[210:211], off offset:2816
	global_load_dword v150, v[210:211], off offset:3072
	global_load_dword v151, v[210:211], off offset:3328
	global_load_dword v152, v[210:211], off offset:3584
; __global__ void __launch_bounds__(512, 2) mega(Params p) {
;     ...
;             for (int c0 = 0; c0 < 64; c0 += 16) { float sr[16], si[16];
; #pragma unroll
;                 for (int k = 0; k < 16; ++k) { sr[k] = Sp[(size_t)(c0 + k) * 128]; si[k] = Sp[(size_t)(c0 + k) * 128 + 64]; }
; #pragma unroll
;                 for (int k = 0; k < 16; ++k) { const float n_r = c_r * hr - c_i * hi + sr[k], n_i = c_r * hi + c_i * hr + si[k]; hr = n_r; hi = n_i; } }
	global_load_dword v153, v[210:211], off offset:3840
	global_load_dword v154, v[212:213], off
	global_load_dword v155, v[212:213], off offset:256
	global_load_dword v156, v[212:213], off offset:512
	global_load_dword v157, v[212:213], off offset:768
	global_load_dword v158, v[212:213], off offset:1024
	global_load_dword v159, v[212:213], off offset:1280
	global_load_dword v160, v[212:213], off offset:1536
	global_load_dword v161, v[212:213], off offset:1792
	global_load_dword v162, v[212:213], off offset:2048
	global_load_dword v163, v[212:213], off offset:2304
	global_load_dword v164, v[212:213], off offset:2560
	global_load_dword v165, v[212:213], off offset:2816
	global_load_dword v166, v[212:213], off offset:3072
	global_load_dword v167, v[212:213], off offset:3328
	global_load_dword v168, v[212:213], off offset:3584
	global_load_dword v169, v[212:213], off offset:3840
	global_load_dword v170, v[214:215], off
	global_load_dword v171, v[214:215], off offset:256
	global_load_dword v172, v[214:215], off offset:512
	global_load_dword v173, v[214:215], off offset:768
	global_load_dword v174, v[214:215], off offset:1024
	global_load_dword v175, v[214:215], off offset:1280
	global_load_dword v176, v[214:215], off offset:1536
	global_load_dword v177, v[214:215], off offset:1792
	global_load_dword v178, v[214:215], off offset:2048
	global_load_dword v179, v[214:215], off offset:2304
	global_load_dword v180, v[214:215], off offset:2560
	global_load_dword v181, v[214:215], off offset:2816
	global_load_dword v182, v[214:215], off offset:3072
	global_load_dword v183, v[214:215], off offset:3328
	global_load_dword v184, v[214:215], off offset:3584
	global_load_dword v185, v[214:215], off offset:3840
	s_waitcnt vmcnt(63)
	v_mul_f32_e32 v8, v1, v7
	v_mul_f32_e32 v9, v1, v6
	v_fma_f32 v8, v0, v6, -v8
	v_fma_f32 v9, v0, v7, v9
	v_add_f32_e32 v6, v8, v54
	v_add_f32_e32 v7, v9, v55
	v_mul_f32_e32 v8, v1, v7
	v_mul_f32_e32 v9, v1, v6
	v_fma_f32 v8, v0, v6, -v8
	v_fma_f32 v9, v0, v7, v9
	v_add_f32_e32 v6, v8, v56
	v_add_f32_e32 v7, v9, v57
	v_mul_f32_e32 v8, v1, v7
	v_mul_f32_e32 v9, v1, v6
	v_fma_f32 v8, v0, v6, -v8
	v_fma_f32 v9, v0, v7, v9
	v_add_f32_e32 v6, v8, v58
	v_add_f32_e32 v7, v9, v59
	v_mul_f32_e32 v8, v1, v7
	v_mul_f32_e32 v9, v1, v6
	v_fma_f32 v8, v0, v6, -v8
	v_fma_f32 v9, v0, v7, v9
	v_add_f32_e32 v6, v8, v60
	v_add_f32_e32 v7, v9, v61
	v_mul_f32_e32 v8, v1, v7
	v_mul_f32_e32 v9, v1, v6
	v_fma_f32 v8, v0, v6, -v8
	v_fma_f32 v9, v0, v7, v9
	v_add_f32_e32 v6, v8, v62
	v_add_f32_e32 v7, v9, v63
	v_mul_f32_e32 v8, v1, v7
	v_mul_f32_e32 v9, v1, v6
	v_fma_f32 v8, v0, v6, -v8
	v_fma_f32 v9, v0, v7, v9
	v_add_f32_e32 v6, v8, v64
	v_add_f32_e32 v7, v9, v65
	v_mul_f32_e32 v8, v1, v7
	v_mul_f32_e32 v9, v1, v6
	v_fma_f32 v8, v0, v6, -v8
	v_fma_f32 v9, v0, v7, v9
	v_add_f32_e32 v6, v8, v66
	v_add_f32_e32 v7, v9, v67
	v_mul_f32_e32 v8, v1, v7
	v_mul_f32_e32 v9, v1, v6
	v_fma_f32 v8, v0, v6, -v8
	v_fma_f32 v9, v0, v7, v9
	v_add_f32_e32 v6, v8, v68
	v_add_f32_e32 v7, v9, v69
	v_mul_f32_e32 v8, v1, v7
	v_mul_f32_e32 v9, v1, v6
	v_fma_f32 v8, v0, v6, -v8
	v_fma_f32 v9, v0, v7, v9
	v_add_f32_e32 v6, v8, v70
	v_add_f32_e32 v7, v9, v71
	v_mul_f32_e32 v8, v1, v7
	v_mul_f32_e32 v9, v1, v6
	v_fma_f32 v8, v0, v6, -v8
	v_fma_f32 v9, v0, v7, v9
	v_add_f32_e32 v6, v8, v72
	v_add_f32_e32 v7, v9, v73
	v_mul_f32_e32 v8, v1, v7
	v_mul_f32_e32 v9, v1, v6
	v_fma_f32 v8, v0, v6, -v8
	v_fma_f32 v9, v0, v7, v9
	v_add_f32_e32 v6, v8, v74
	v_add_f32_e32 v7, v9, v75
	v_mul_f32_e32 v8, v1, v7
	v_mul_f32_e32 v9, v1, v6
	v_fma_f32 v8, v0, v6, -v8
	v_fma_f32 v9, v0, v7, v9
	v_add_f32_e32 v6, v8, v76
	v_add_f32_e32 v7, v9, v77
	v_mul_f32_e32 v8, v1, v7
	v_mul_f32_e32 v9, v1, v6
	v_fma_f32 v8, v0, v6, -v8
	v_fma_f32 v9, v0, v7, v9
	v_add_f32_e32 v6, v8, v78
	v_add_f32_e32 v7, v9, v79
	v_mul_f32_e32 v8, v1, v7
	v_mul_f32_e32 v9, v1, v6
	v_fma_f32 v8, v0, v6, -v8
	v_fma_f32 v9, v0, v7, v9
	v_add_f32_e32 v6, v8, v80
	v_add_f32_e32 v7, v9, v81
	v_mul_f32_e32 v8, v1, v7
	v_mul_f32_e32 v9, v1, v6
	v_fma_f32 v8, v0, v6, -v8
	v_fma_f32 v9, v0, v7, v9
	v_add_f32_e32 v6, v8, v82
	v_add_f32_e32 v7, v9, v83
	v_mul_f32_e32 v8, v1, v7
	v_mul_f32_e32 v9, v1, v6
	v_fma_f32 v8, v0, v6, -v8
	v_fma_f32 v9, v0, v7, v9
	v_add_f32_e32 v6, v8, v84
	v_add_f32_e32 v7, v9, v85
	v_mul_f32_e32 v8, v1, v7
	v_mul_f32_e32 v9, v1, v6
	v_fma_f32 v8, v0, v6, -v8
	v_fma_f32 v9, v0, v7, v9
	v_add_f32_e32 v6, v8, v86
	v_add_f32_e32 v7, v9, v87
	v_mul_f32_e32 v8, v1, v7
	v_mul_f32_e32 v9, v1, v6
	v_fma_f32 v8, v0, v6, -v8
	v_fma_f32 v9, v0, v7, v9
	v_add_f32_e32 v6, v8, v88
	v_add_f32_e32 v7, v9, v89
	v_mul_f32_e32 v8, v1, v7
	v_mul_f32_e32 v9, v1, v6
	v_fma_f32 v8, v0, v6, -v8
	v_fma_f32 v9, v0, v7, v9
	v_add_f32_e32 v6, v8, v90
	v_add_f32_e32 v7, v9, v91
	v_mul_f32_e32 v8, v1, v7
	v_mul_f32_e32 v9, v1, v6
	v_fma_f32 v8, v0, v6, -v8
	v_fma_f32 v9, v0, v7, v9
	v_add_f32_e32 v6, v8, v92
	v_add_f32_e32 v7, v9, v93
	v_mul_f32_e32 v8, v1, v7
	v_mul_f32_e32 v9, v1, v6
	v_fma_f32 v8, v0, v6, -v8
	v_fma_f32 v9, v0, v7, v9
	v_add_f32_e32 v6, v8, v94
	v_add_f32_e32 v7, v9, v95
	v_mul_f32_e32 v8, v1, v7
	v_mul_f32_e32 v9, v1, v6
	v_fma_f32 v8, v0, v6, -v8
	v_fma_f32 v9, v0, v7, v9
	v_add_f32_e32 v6, v8, v96
	v_add_f32_e32 v7, v9, v97
	v_mul_f32_e32 v8, v1, v7
	v_mul_f32_e32 v9, v1, v6
	v_fma_f32 v8, v0, v6, -v8
	v_fma_f32 v9, v0, v7, v9
	v_add_f32_e32 v6, v8, v98
	v_add_f32_e32 v7, v9, v99
	v_mul_f32_e32 v8, v1, v7
	v_mul_f32_e32 v9, v1, v6
	v_fma_f32 v8, v0, v6, -v8
	v_fma_f32 v9, v0, v7, v9
	v_add_f32_e32 v6, v8, v100
	v_add_f32_e32 v7, v9, v101
	v_mul_f32_e32 v8, v1, v7
	v_mul_f32_e32 v9, v1, v6
	v_fma_f32 v8, v0, v6, -v8
	v_fma_f32 v9, v0, v7, v9
	v_add_f32_e32 v6, v8, v102
	v_add_f32_e32 v7, v9, v103
	v_mul_f32_e32 v8, v1, v7
	v_mul_f32_e32 v9, v1, v6
	v_fma_f32 v8, v0, v6, -v8
	v_fma_f32 v9, v0, v7, v9
	v_add_f32_e32 v6, v8, v104
	v_add_f32_e32 v7, v9, v105
	v_mul_f32_e32 v8, v1, v7
	v_mul_f32_e32 v9, v1, v6
	v_fma_f32 v8, v0, v6, -v8
	v_fma_f32 v9, v0, v7, v9
	v_add_f32_e32 v6, v8, v106
	v_add_f32_e32 v7, v9, v107
	v_mul_f32_e32 v8, v1, v7
	v_mul_f32_e32 v9, v1, v6
	v_fma_f32 v8, v0, v6, -v8
	v_fma_f32 v9, v0, v7, v9
	v_add_f32_e32 v6, v8, v108
	v_add_f32_e32 v7, v9, v109
	v_mul_f32_e32 v8, v1, v7
	v_mul_f32_e32 v9, v1, v6
	v_fma_f32 v8, v0, v6, -v8
	v_fma_f32 v9, v0, v7, v9
	v_add_f32_e32 v6, v8, v110
	v_add_f32_e32 v7, v9, v111
	v_mul_f32_e32 v8, v1, v7
	v_mul_f32_e32 v9, v1, v6
	v_fma_f32 v8, v0, v6, -v8
	v_fma_f32 v9, v0, v7, v9
	v_add_f32_e32 v6, v8, v112
	v_add_f32_e32 v7, v9, v113
	v_mul_f32_e32 v8, v1, v7
	v_mul_f32_e32 v9, v1, v6
	v_fma_f32 v8, v0, v6, -v8
	v_fma_f32 v9, v0, v7, v9
	v_add_f32_e32 v6, v8, v114
	v_add_f32_e32 v7, v9, v115
	v_mul_f32_e32 v8, v1, v7
	v_mul_f32_e32 v9, v1, v6
	v_fma_f32 v8, v0, v6, -v8
	v_fma_f32 v9, v0, v7, v9
	v_add_f32_e32 v6, v8, v116
	v_add_f32_e32 v7, v9, v117
	s_waitcnt vmcnt(62)
; __global__ void __launch_bounds__(512, 2) mega(Params p) {
;     ...
;             for (int c0 = 0; c0 < 64; c0 += 16) { float sr[16], si[16];
; #pragma unroll
;                 for (int k = 0; k < 16; ++k) { sr[k] = Sp[(size_t)(c0 + k) * 128]; si[k] = Sp[(size_t)(c0 + k) * 128 + 64]; }
; #pragma unroll
;                 for (int k = 0; k < 16; ++k) { const float n_r = c_r * hr - c_i * hi + sr[k], n_i = c_r * hi + c_i * hr + si[k]; hr = n_r; hi = n_i; } }
;             ex[(wave * 64 + lane) * 2] = hr; ex[(wave * 64 + lane) * 2 + 1] = hi;
	v_mul_f32_e32 v8, v1, v7
	v_mul_f32_e32 v9, v1, v6
	v_fma_f32 v8, v0, v6, -v8
	v_fma_f32 v9, v0, v7, v9
	v_add_f32_e32 v6, v8, v118
	v_add_f32_e32 v7, v9, v119
	s_waitcnt vmcnt(60)
	v_mul_f32_e32 v8, v1, v7
	v_mul_f32_e32 v9, v1, v6
	v_fma_f32 v8, v0, v6, -v8
	v_fma_f32 v9, v0, v7, v9
	v_add_f32_e32 v6, v8, v120
	v_add_f32_e32 v7, v9, v121
	s_waitcnt vmcnt(58)
	v_mul_f32_e32 v8, v1, v7
	v_mul_f32_e32 v9, v1, v6
	v_fma_f32 v8, v0, v6, -v8
	v_fma_f32 v9, v0, v7, v9
	v_add_f32_e32 v6, v8, v122
	v_add_f32_e32 v7, v9, v123
	s_waitcnt vmcnt(56)
	v_mul_f32_e32 v8, v1, v7
	v_mul_f32_e32 v9, v1, v6
	v_fma_f32 v8, v0, v6, -v8
	v_fma_f32 v9, v0, v7, v9
	v_add_f32_e32 v6, v8, v124
	v_add_f32_e32 v7, v9, v125
	s_waitcnt vmcnt(54)
	v_mul_f32_e32 v8, v1, v7
	v_mul_f32_e32 v9, v1, v6
	v_fma_f32 v8, v0, v6, -v8
	v_fma_f32 v9, v0, v7, v9
	v_add_f32_e32 v6, v8, v130
	v_add_f32_e32 v7, v9, v131
	s_waitcnt vmcnt(52)
	v_mul_f32_e32 v8, v1, v7
	v_mul_f32_e32 v9, v1, v6
	v_fma_f32 v8, v0, v6, -v8
	v_fma_f32 v9, v0, v7, v9
	v_add_f32_e32 v6, v8, v132
	v_add_f32_e32 v7, v9, v133
	s_waitcnt vmcnt(50)
	v_mul_f32_e32 v8, v1, v7
	v_mul_f32_e32 v9, v1, v6
	v_fma_f32 v8, v0, v6, -v8
	v_fma_f32 v9, v0, v7, v9
	v_add_f32_e32 v6, v8, v134
	v_add_f32_e32 v7, v9, v135
	s_waitcnt vmcnt(48)
	v_mul_f32_e32 v8, v1, v7
	v_mul_f32_e32 v9, v1, v6
	v_fma_f32 v8, v0, v6, -v8
	v_fma_f32 v9, v0, v7, v9
	v_add_f32_e32 v6, v8, v136
	v_add_f32_e32 v7, v9, v137
	s_waitcnt vmcnt(46)
	v_mul_f32_e32 v8, v1, v7
	v_mul_f32_e32 v9, v1, v6
	v_fma_f32 v8, v0, v6, -v8
	v_fma_f32 v9, v0, v7, v9
	v_add_f32_e32 v6, v8, v138
	v_add_f32_e32 v7, v9, v139
	s_waitcnt vmcnt(44)
	v_mul_f32_e32 v8, v1, v7
	v_mul_f32_e32 v9, v1, v6
	v_fma_f32 v8, v0, v6, -v8
	v_fma_f32 v9, v0, v7, v9
	v_add_f32_e32 v6, v8, v140
	v_add_f32_e32 v7, v9, v141
	s_waitcnt vmcnt(42)
	v_mul_f32_e32 v8, v1, v7
	v_mul_f32_e32 v9, v1, v6
	v_fma_f32 v8, v0, v6, -v8
	v_fma_f32 v9, v0, v7, v9
	v_add_f32_e32 v6, v8, v142
	v_add_f32_e32 v7, v9, v143
	s_waitcnt vmcnt(40)
	v_mul_f32_e32 v8, v1, v7
	v_mul_f32_e32 v9, v1, v6
	v_fma_f32 v8, v0, v6, -v8
	v_fma_f32 v9, v0, v7, v9
	v_add_f32_e32 v6, v8, v144
	v_add_f32_e32 v7, v9, v145
	s_waitcnt vmcnt(38)
	v_mul_f32_e32 v8, v1, v7
	v_mul_f32_e32 v9, v1, v6
	v_fma_f32 v8, v0, v6, -v8
	v_fma_f32 v9, v0, v7, v9
	v_add_f32_e32 v6, v8, v146
	v_add_f32_e32 v7, v9, v147
	s_waitcnt vmcnt(36)
	v_mul_f32_e32 v8, v1, v7
	v_mul_f32_e32 v9, v1, v6
	v_fma_f32 v8, v0, v6, -v8
	v_fma_f32 v9, v0, v7, v9
	v_add_f32_e32 v6, v8, v148
	v_add_f32_e32 v7, v9, v149
	s_waitcnt vmcnt(34)
	v_mul_f32_e32 v8, v1, v7
	v_mul_f32_e32 v9, v1, v6
	v_fma_f32 v8, v0, v6, -v8
	v_fma_f32 v9, v0, v7, v9
	v_add_f32_e32 v6, v8, v150
	v_add_f32_e32 v7, v9, v151
	s_waitcnt vmcnt(32)
	v_mul_f32_e32 v8, v1, v7
	v_mul_f32_e32 v9, v1, v6
	v_fma_f32 v8, v0, v6, -v8
	v_fma_f32 v9, v0, v7, v9
	v_add_f32_e32 v6, v8, v152
	v_add_f32_e32 v7, v9, v153
	s_waitcnt vmcnt(30)
	v_mul_f32_e32 v8, v1, v7
	v_mul_f32_e32 v9, v1, v6
	v_fma_f32 v8, v0, v6, -v8
	v_fma_f32 v9, v0, v7, v9
	v_add_f32_e32 v6, v8, v154
	v_add_f32_e32 v7, v9, v155
	s_waitcnt vmcnt(28)
	v_mul_f32_e32 v8, v1, v7
	v_mul_f32_e32 v9, v1, v6
	v_fma_f32 v8, v0, v6, -v8
	v_fma_f32 v9, v0, v7, v9
	v_add_f32_e32 v6, v8, v156
	v_add_f32_e32 v7, v9, v157
	s_waitcnt vmcnt(26)
	v_mul_f32_e32 v8, v1, v7
	v_mul_f32_e32 v9, v1, v6
	v_fma_f32 v8, v0, v6, -v8
	v_fma_f32 v9, v0, v7, v9
	v_add_f32_e32 v6, v8, v158
	v_add_f32_e32 v7, v9, v159
	s_waitcnt vmcnt(24)
	v_mul_f32_e32 v8, v1, v7
	v_mul_f32_e32 v9, v1, v6
	v_fma_f32 v8, v0, v6, -v8
	v_fma_f32 v9, v0, v7, v9
	v_add_f32_e32 v6, v8, v160
	v_add_f32_e32 v7, v9, v161
	s_waitcnt vmcnt(22)
	v_mul_f32_e32 v8, v1, v7
	v_mul_f32_e32 v9, v1, v6
	v_fma_f32 v8, v0, v6, -v8
	v_fma_f32 v9, v0, v7, v9
	v_add_f32_e32 v6, v8, v162
	v_add_f32_e32 v7, v9, v163
	s_waitcnt vmcnt(20)
	v_mul_f32_e32 v8, v1, v7
	v_mul_f32_e32 v9, v1, v6
	v_fma_f32 v8, v0, v6, -v8
	v_fma_f32 v9, v0, v7, v9
	v_add_f32_e32 v6, v8, v164
	v_add_f32_e32 v7, v9, v165
	s_waitcnt vmcnt(18)
	v_mul_f32_e32 v8, v1, v7
	v_mul_f32_e32 v9, v1, v6
	v_fma_f32 v8, v0, v6, -v8
	v_fma_f32 v9, v0, v7, v9
	v_add_f32_e32 v6, v8, v166
	v_add_f32_e32 v7, v9, v167
	s_waitcnt vmcnt(16)
	v_mul_f32_e32 v8, v1, v7
	v_mul_f32_e32 v9, v1, v6
	v_fma_f32 v8, v0, v6, -v8
	v_fma_f32 v9, v0, v7, v9
	v_add_f32_e32 v6, v8, v168
	v_add_f32_e32 v7, v9, v169
	s_waitcnt vmcnt(14)
	v_mul_f32_e32 v8, v1, v7
	v_mul_f32_e32 v9, v1, v6
	v_fma_f32 v8, v0, v6, -v8
	v_fma_f32 v9, v0, v7, v9
	v_add_f32_e32 v6, v8, v170
	v_add_f32_e32 v7, v9, v171
	s_waitcnt vmcnt(12)
	v_mul_f32_e32 v8, v1, v7
	v_mul_f32_e32 v9, v1, v6
	v_fma_f32 v8, v0, v6, -v8
	v_fma_f32 v9, v0, v7, v9
	v_add_f32_e32 v6, v8, v172
	v_add_f32_e32 v7, v9, v173
	s_waitcnt vmcnt(10)
	v_mul_f32_e32 v8, v1, v7
	v_mul_f32_e32 v9, v1, v6
	v_fma_f32 v8, v0, v6, -v8
	v_fma_f32 v9, v0, v7, v9
	v_add_f32_e32 v6, v8, v174
	v_add_f32_e32 v7, v9, v175
	s_waitcnt vmcnt(8)
	v_mul_f32_e32 v8, v1, v7
	v_mul_f32_e32 v9, v1, v6
	v_fma_f32 v8, v0, v6, -v8
	v_fma_f32 v9, v0, v7, v9
	v_add_f32_e32 v6, v8, v176
	v_add_f32_e32 v7, v9, v177
	s_waitcnt vmcnt(6)
	v_mul_f32_e32 v8, v1, v7
	v_mul_f32_e32 v9, v1, v6
	v_fma_f32 v8, v0, v6, -v8
	v_fma_f32 v9, v0, v7, v9
	v_add_f32_e32 v6, v8, v178
	v_add_f32_e32 v7, v9, v179
	s_waitcnt vmcnt(4)
	v_mul_f32_e32 v8, v1, v7
	v_mul_f32_e32 v9, v1, v6
	v_fma_f32 v8, v0, v6, -v8
	v_fma_f32 v9, v0, v7, v9
	v_add_f32_e32 v6, v8, v180
	v_add_f32_e32 v7, v9, v181
	s_waitcnt vmcnt(2)
	v_mul_f32_e32 v8, v1, v7
	v_mul_f32_e32 v9, v1, v6
	v_fma_f32 v8, v0, v6, -v8
	v_fma_f32 v9, v0, v7, v9
	v_add_f32_e32 v6, v8, v182
	v_add_f32_e32 v7, v9, v183
	s_waitcnt vmcnt(0)
	v_mul_f32_e32 v8, v1, v7
	v_mul_f32_e32 v9, v1, v6
	v_fma_f32 v8, v0, v6, -v8
	v_fma_f32 v9, v0, v7, v9
	v_add_f32_e32 v6, v8, v184
	v_add_f32_e32 v7, v9, v185
	v_add_u32_e32 v2, s77, v128
	v_lshl_add_u32 v2, v2, 3, 0
	ds_write_b64 v2, v[6:7]
	s_branch .LBB0_673

; __global__ void __launch_bounds__(512, 2) mega(Params p) {
;     ...
;             for (int c0 = 0; c0 < 64; c0 += 16) { float sr[16], si[16];
; #pragma unroll
;                 for (int k = 0; k < 16; ++k) { sr[k] = Sp[(size_t)(c0 + k) * 128]; si[k] = Sp[(size_t)(c0 + k) * 128 + 64]; }
; #pragma unroll
;                 for (int k = 0; k < 16; ++k) { const unsigned w = pk2(hr, hi); Hp[(size_t)(c0 + k) * 384] = (bf16_t)(w & 0xffffu); Hp[(size_t)(c0 + k) * 384 + 64] = (bf16_t)(w >> 16);
;                     const float n_r = c_r * hr - c_i * hi + sr[k], n_i = c_r * hi + c_i * hr + si[k]; hr = n_r; hi = n_i; } }
;             if (wave == 7) { float* o = p.out + O_S5P + (((size_t)b * 32 + g) * 64 + lane) * 2; o[0] = hr; o[1] = hi; }
.LBB0_683:
	v_lshl_add_u64 v[216:217], s[90:91], 0, v[10:11]
	v_add_co_u32_e32 v216, vcc, 0x14800000, v216
	s_nop 1
	v_addc_co_u32_e32 v217, vcc, 0, v217, vcc
	v_cvt_pk_bf16_f32 v218, v12, v12
	v_cvt_pk_bf16_f32 v219, v13, v13
	global_store_short v[216:217], v218, off
	global_store_short v[216:217], v219, off offset:128
	v_mul_f32_e32 v220, v1, v13
	v_mul_f32_e32 v221, v1, v12
	v_fma_f32 v220, v0, v12, -v220
	v_fma_f32 v221, v0, v13, v221
	v_add_f32_e32 v12, v220, v54
	v_add_f32_e32 v13, v221, v55
	v_cvt_pk_bf16_f32 v222, v12, v12
	v_cvt_pk_bf16_f32 v223, v13, v13
	global_store_short v[216:217], v222, off offset:768
	global_store_short v[216:217], v223, off offset:896
	v_mul_f32_e32 v220, v1, v13
	v_mul_f32_e32 v221, v1, v12
	v_fma_f32 v220, v0, v12, -v220
	v_fma_f32 v221, v0, v13, v221
	v_add_f32_e32 v12, v220, v56
	v_add_f32_e32 v13, v221, v57
	v_cvt_pk_bf16_f32 v218, v12, v12
	v_cvt_pk_bf16_f32 v219, v13, v13
	global_store_short v[216:217], v218, off offset:1536
	global_store_short v[216:217], v219, off offset:1664
	v_mul_f32_e32 v220, v1, v13
	v_mul_f32_e32 v221, v1, v12
	v_fma_f32 v220, v0, v12, -v220
	v_fma_f32 v221, v0, v13, v221
	v_add_f32_e32 v12, v220, v58
	v_add_f32_e32 v13, v221, v59
	v_cvt_pk_bf16_f32 v222, v12, v12
	v_cvt_pk_bf16_f32 v223, v13, v13
	global_store_short v[216:217], v222, off offset:2304
	global_store_short v[216:217], v223, off offset:2432
	v_mul_f32_e32 v220, v1, v13
	v_mul_f32_e32 v221, v1, v12
	v_fma_f32 v220, v0, v12, -v220
	v_fma_f32 v221, v0, v13, v221
	v_add_f32_e32 v12, v220, v60
	v_add_f32_e32 v13, v221, v61
	v_add_co_u32_e32 v216, vcc, 0xc00, v216
	s_nop 1
	v_addc_co_u32_e32 v217, vcc, 0, v217, vcc
	v_cvt_pk_bf16_f32 v218, v12, v12
	v_cvt_pk_bf16_f32 v219, v13, v13
	global_store_short v[216:217], v218, off
	global_store_short v[216:217], v219, off offset:128
	v_mul_f32_e32 v220, v1, v13
	v_mul_f32_e32 v221, v1, v12
	v_fma_f32 v220, v0, v12, -v220
	v_fma_f32 v221, v0, v13, v221
	v_add_f32_e32 v12, v220, v62
	v_add_f32_e32 v13, v221, v63
	v_cvt_pk_bf16_f32 v222, v12, v12
	v_cvt_pk_bf16_f32 v223, v13, v13
	global_store_short v[216:217], v222, off offset:768
	global_store_short v[216:217], v223, off offset:896
	v_mul_f32_e32 v220, v1, v13
	v_mul_f32_e32 v221, v1, v12
	v_fma_f32 v220, v0, v12, -v220
	v_fma_f32 v221, v0, v13, v221
	v_add_f32_e32 v12, v220, v64
	v_add_f32_e32 v13, v221, v65
	v_cvt_pk_bf16_f32 v218, v12, v12
	v_cvt_pk_bf16_f32 v219, v13, v13
	global_store_short v[216:217], v218, off offset:1536
	global_store_short v[216:217], v219, off offset:1664
	v_mul_f32_e32 v220, v1, v13
	v_mul_f32_e32 v221, v1, v12
	v_fma_f32 v220, v0, v12, -v220
	v_fma_f32 v221, v0, v13, v221
	v_add_f32_e32 v12, v220, v66
	v_add_f32_e32 v13, v221, v67
	v_cvt_pk_bf16_f32 v222, v12, v12
	v_cvt_pk_bf16_f32 v223, v13, v13
	global_store_short v[216:217], v222, off offset:2304
	global_store_short v[216:217], v223, off offset:2432
	v_mul_f32_e32 v220, v1, v13
	v_mul_f32_e32 v221, v1, v12
	v_fma_f32 v220, v0, v12, -v220
	v_fma_f32 v221, v0, v13, v221
	v_add_f32_e32 v12, v220, v68
	v_add_f32_e32 v13, v221, v69
	v_add_co_u32_e32 v216, vcc, 0xc00, v216
	s_nop 1
	v_addc_co_u32_e32 v217, vcc, 0, v217, vcc
	v_cvt_pk_bf16_f32 v218, v12, v12
	v_cvt_pk_bf16_f32 v219, v13, v13
	global_store_short v[216:217], v218, off
	global_store_short v[216:217], v219, off offset:128
	v_mul_f32_e32 v220, v1, v13
	v_mul_f32_e32 v221, v1, v12
	v_fma_f32 v220, v0, v12, -v220
	v_fma_f32 v221, v0, v13, v221
	v_add_f32_e32 v12, v220, v70
	v_add_f32_e32 v13, v221, v71
	v_cvt_pk_bf16_f32 v222, v12, v12
	v_cvt_pk_bf16_f32 v223, v13, v13
	global_store_short v[216:217], v222, off offset:768
	global_store_short v[216:217], v223, off offset:896
	v_mul_f32_e32 v220, v1, v13
	v_mul_f32_e32 v221, v1, v12
	v_fma_f32 v220, v0, v12, -v220
	v_fma_f32 v221, v0, v13, v221
	v_add_f32_e32 v12, v220, v72
	v_add_f32_e32 v13, v221, v73
	v_cvt_pk_bf16_f32 v218, v12, v12
	v_cvt_pk_bf16_f32 v219, v13, v13
	global_store_short v[216:217], v218, off offset:1536
	global_store_short v[216:217], v219, off offset:1664
	v_mul_f32_e32 v220, v1, v13
	v_mul_f32_e32 v221, v1, v12
	v_fma_f32 v220, v0, v12, -v220
	v_fma_f32 v221, v0, v13, v221
	v_add_f32_e32 v12, v220, v74
	v_add_f32_e32 v13, v221, v75
	v_cvt_pk_bf16_f32 v222, v12, v12
	v_cvt_pk_bf16_f32 v223, v13, v13
	global_store_short v[216:217], v222, off offset:2304
	global_store_short v[216:217], v223, off offset:2432
	v_mul_f32_e32 v220, v1, v13
	v_mul_f32_e32 v221, v1, v12
	v_fma_f32 v220, v0, v12, -v220
	v_fma_f32 v221, v0, v13, v221
	v_add_f32_e32 v12, v220, v76
	v_add_f32_e32 v13, v221, v77
	v_add_co_u32_e32 v216, vcc, 0xc00, v216
	s_nop 1
	v_addc_co_u32_e32 v217, vcc, 0, v217, vcc
	v_cvt_pk_bf16_f32 v218, v12, v12
	v_cvt_pk_bf16_f32 v219, v13, v13
	global_store_short v[216:217], v218, off
	global_store_short v[216:217], v219, off offset:128
	v_mul_f32_e32 v220, v1, v13
	v_mul_f32_e32 v221, v1, v12
	v_fma_f32 v220, v0, v12, -v220
	v_fma_f32 v221, v0, v13, v221
	v_add_f32_e32 v12, v220, v78
	v_add_f32_e32 v13, v221, v79
	v_cvt_pk_bf16_f32 v222, v12, v12
	v_cvt_pk_bf16_f32 v223, v13, v13
	global_store_short v[216:217], v222, off offset:768
	global_store_short v[216:217], v223, off offset:896
	v_mul_f32_e32 v220, v1, v13
	v_mul_f32_e32 v221, v1, v12
	v_fma_f32 v220, v0, v12, -v220
	v_fma_f32 v221, v0, v13, v221
	v_add_f32_e32 v12, v220, v80
	v_add_f32_e32 v13, v221, v81
	v_cvt_pk_bf16_f32 v218, v12, v12
	v_cvt_pk_bf16_f32 v219, v13, v13
	global_store_short v[216:217], v218, off offset:1536
	global_store_short v[216:217], v219, off offset:1664
	v_mul_f32_e32 v220, v1, v13
	v_mul_f32_e32 v221, v1, v12
	v_fma_f32 v220, v0, v12, -v220
; __global__ void __launch_bounds__(512, 2) mega(Params p) {
;     ...
;             for (int c0 = 0; c0 < 64; c0 += 16) { float sr[16], si[16];
; #pragma unroll
;                 for (int k = 0; k < 16; ++k) { sr[k] = Sp[(size_t)(c0 + k) * 128]; si[k] = Sp[(size_t)(c0 + k) * 128 + 64]; }
; #pragma unroll
;                 for (int k = 0; k < 16; ++k) { const unsigned w = pk2(hr, hi); Hp[(size_t)(c0 + k) * 384] = (bf16_t)(w & 0xffffu); Hp[(size_t)(c0 + k) * 384 + 64] = (bf16_t)(w >> 16);
;                     const float n_r = c_r * hr - c_i * hi + sr[k], n_i = c_r * hi + c_i * hr + si[k]; hr = n_r; hi = n_i; } }
;             if (wave == 7) { float* o = p.out + O_S5P + (((size_t)b * 32 + g) * 64 + lane) * 2; o[0] = hr; o[1] = hi; }
	v_fma_f32 v221, v0, v13, v221
	v_add_f32_e32 v12, v220, v82
	v_add_f32_e32 v13, v221, v83
	v_cvt_pk_bf16_f32 v222, v12, v12
	v_cvt_pk_bf16_f32 v223, v13, v13
	global_store_short v[216:217], v222, off offset:2304
	global_store_short v[216:217], v223, off offset:2432
	v_mul_f32_e32 v220, v1, v13
	v_mul_f32_e32 v221, v1, v12
	v_fma_f32 v220, v0, v12, -v220
	v_fma_f32 v221, v0, v13, v221
	v_add_f32_e32 v12, v220, v84
	v_add_f32_e32 v13, v221, v85
	v_add_co_u32_e32 v216, vcc, 0xc00, v216
	s_nop 1
	v_addc_co_u32_e32 v217, vcc, 0, v217, vcc
	v_cvt_pk_bf16_f32 v218, v12, v12
	v_cvt_pk_bf16_f32 v219, v13, v13
	global_store_short v[216:217], v218, off
	global_store_short v[216:217], v219, off offset:128
	v_mul_f32_e32 v220, v1, v13
	v_mul_f32_e32 v221, v1, v12
	v_fma_f32 v220, v0, v12, -v220
	v_fma_f32 v221, v0, v13, v221
	v_add_f32_e32 v12, v220, v86
	v_add_f32_e32 v13, v221, v87
	v_cvt_pk_bf16_f32 v222, v12, v12
	v_cvt_pk_bf16_f32 v223, v13, v13
	global_store_short v[216:217], v222, off offset:768
	global_store_short v[216:217], v223, off offset:896
	v_mul_f32_e32 v220, v1, v13
	v_mul_f32_e32 v221, v1, v12
	v_fma_f32 v220, v0, v12, -v220
	v_fma_f32 v221, v0, v13, v221
	v_add_f32_e32 v12, v220, v88
	v_add_f32_e32 v13, v221, v89
	v_cvt_pk_bf16_f32 v218, v12, v12
	v_cvt_pk_bf16_f32 v219, v13, v13
	global_store_short v[216:217], v218, off offset:1536
	global_store_short v[216:217], v219, off offset:1664
	v_mul_f32_e32 v220, v1, v13
	v_mul_f32_e32 v221, v1, v12
	v_fma_f32 v220, v0, v12, -v220
	v_fma_f32 v221, v0, v13, v221
	v_add_f32_e32 v12, v220, v90
	v_add_f32_e32 v13, v221, v91
	v_cvt_pk_bf16_f32 v222, v12, v12
	v_cvt_pk_bf16_f32 v223, v13, v13
	global_store_short v[216:217], v222, off offset:2304
	global_store_short v[216:217], v223, off offset:2432
	v_mul_f32_e32 v220, v1, v13
	v_mul_f32_e32 v221, v1, v12
	v_fma_f32 v220, v0, v12, -v220
	v_fma_f32 v221, v0, v13, v221
	v_add_f32_e32 v12, v220, v92
	v_add_f32_e32 v13, v221, v93
	v_add_co_u32_e32 v216, vcc, 0xc00, v216
	s_nop 1
	v_addc_co_u32_e32 v217, vcc, 0, v217, vcc
	v_cvt_pk_bf16_f32 v218, v12, v12
	v_cvt_pk_bf16_f32 v219, v13, v13
	global_store_short v[216:217], v218, off
	global_store_short v[216:217], v219, off offset:128
	v_mul_f32_e32 v220, v1, v13
	v_mul_f32_e32 v221, v1, v12
	v_fma_f32 v220, v0, v12, -v220
	v_fma_f32 v221, v0, v13, v221
	v_add_f32_e32 v12, v220, v94
	v_add_f32_e32 v13, v221, v95
	v_cvt_pk_bf16_f32 v222, v12, v12
	v_cvt_pk_bf16_f32 v223, v13, v13
	global_store_short v[216:217], v222, off offset:768
	global_store_short v[216:217], v223, off offset:896
	v_mul_f32_e32 v220, v1, v13
	v_mul_f32_e32 v221, v1, v12
	v_fma_f32 v220, v0, v12, -v220
	v_fma_f32 v221, v0, v13, v221
	v_add_f32_e32 v12, v220, v96
	v_add_f32_e32 v13, v221, v97
	v_cvt_pk_bf16_f32 v218, v12, v12
	v_cvt_pk_bf16_f32 v219, v13, v13
	global_store_short v[216:217], v218, off offset:1536
	global_store_short v[216:217], v219, off offset:1664
	v_mul_f32_e32 v220, v1, v13
	v_mul_f32_e32 v221, v1, v12
	v_fma_f32 v220, v0, v12, -v220
	v_fma_f32 v221, v0, v13, v221
	v_add_f32_e32 v12, v220, v98
	v_add_f32_e32 v13, v221, v99
	v_cvt_pk_bf16_f32 v222, v12, v12
	v_cvt_pk_bf16_f32 v223, v13, v13
	global_store_short v[216:217], v222, off offset:2304
	global_store_short v[216:217], v223, off offset:2432
	v_mul_f32_e32 v220, v1, v13
	v_mul_f32_e32 v221, v1, v12
	v_fma_f32 v220, v0, v12, -v220
	v_fma_f32 v221, v0, v13, v221
	v_add_f32_e32 v12, v220, v100
	v_add_f32_e32 v13, v221, v101
	v_add_co_u32_e32 v216, vcc, 0xc00, v216
	s_nop 1
	v_addc_co_u32_e32 v217, vcc, 0, v217, vcc
	v_cvt_pk_bf16_f32 v218, v12, v12
	v_cvt_pk_bf16_f32 v219, v13, v13
	global_store_short v[216:217], v218, off
	global_store_short v[216:217], v219, off offset:128
	v_mul_f32_e32 v220, v1, v13
	v_mul_f32_e32 v221, v1, v12
	v_fma_f32 v220, v0, v12, -v220
	v_fma_f32 v221, v0, v13, v221
	v_add_f32_e32 v12, v220, v102
	v_add_f32_e32 v13, v221, v103
	v_cvt_pk_bf16_f32 v222, v12, v12
	v_cvt_pk_bf16_f32 v223, v13, v13
	global_store_short v[216:217], v222, off offset:768
	global_store_short v[216:217], v223, off offset:896
	v_mul_f32_e32 v220, v1, v13
	v_mul_f32_e32 v221, v1, v12
	v_fma_f32 v220, v0, v12, -v220
	v_fma_f32 v221, v0, v13, v221
	v_add_f32_e32 v12, v220, v104
	v_add_f32_e32 v13, v221, v105
	v_cvt_pk_bf16_f32 v218, v12, v12
	v_cvt_pk_bf16_f32 v219, v13, v13
	global_store_short v[216:217], v218, off offset:1536
	global_store_short v[216:217], v219, off offset:1664
	v_mul_f32_e32 v220, v1, v13
	v_mul_f32_e32 v221, v1, v12
	v_fma_f32 v220, v0, v12, -v220
	v_fma_f32 v221, v0, v13, v221
	v_add_f32_e32 v12, v220, v106
	v_add_f32_e32 v13, v221, v107
	v_cvt_pk_bf16_f32 v222, v12, v12
	v_cvt_pk_bf16_f32 v223, v13, v13
	global_store_short v[216:217], v222, off offset:2304
	global_store_short v[216:217], v223, off offset:2432
	v_mul_f32_e32 v220, v1, v13
	v_mul_f32_e32 v221, v1, v12
	v_fma_f32 v220, v0, v12, -v220
	v_fma_f32 v221, v0, v13, v221
	v_add_f32_e32 v12, v220, v108
	v_add_f32_e32 v13, v221, v109
	v_add_co_u32_e32 v216, vcc, 0xc00, v216
	s_nop 1
	v_addc_co_u32_e32 v217, vcc, 0, v217, vcc
	v_cvt_pk_bf16_f32 v218, v12, v12
	v_cvt_pk_bf16_f32 v219, v13, v13
	global_store_short v[216:217], v218, off
	global_store_short v[216:217], v219, off offset:128
	v_mul_f32_e32 v220, v1, v13
	v_mul_f32_e32 v221, v1, v12
	v_fma_f32 v220, v0, v12, -v220
	v_fma_f32 v221, v0, v13, v221
	v_add_f32_e32 v12, v220, v110
	v_add_f32_e32 v13, v221, v111
	v_cvt_pk_bf16_f32 v222, v12, v12
	v_cvt_pk_bf16_f32 v223, v13, v13
	global_store_short v[216:217], v222, off offset:768
	global_store_short v[216:217], v223, off offset:896
	v_mul_f32_e32 v220, v1, v13
	v_mul_f32_e32 v221, v1, v12
; __global__ void __launch_bounds__(512, 2) mega(Params p) {
;     ...
;             for (int c0 = 0; c0 < 64; c0 += 16) { float sr[16], si[16];
; #pragma unroll
;                 for (int k = 0; k < 16; ++k) { sr[k] = Sp[(size_t)(c0 + k) * 128]; si[k] = Sp[(size_t)(c0 + k) * 128 + 64]; }
; #pragma unroll
;                 for (int k = 0; k < 16; ++k) { const unsigned w = pk2(hr, hi); Hp[(size_t)(c0 + k) * 384] = (bf16_t)(w & 0xffffu); Hp[(size_t)(c0 + k) * 384 + 64] = (bf16_t)(w >> 16);
;                     const float n_r = c_r * hr - c_i * hi + sr[k], n_i = c_r * hi + c_i * hr + si[k]; hr = n_r; hi = n_i; } }
;             if (wave == 7) { float* o = p.out + O_S5P + (((size_t)b * 32 + g) * 64 + lane) * 2; o[0] = hr; o[1] = hi; }
	v_fma_f32 v220, v0, v12, -v220
	v_fma_f32 v221, v0, v13, v221
	v_add_f32_e32 v12, v220, v112
	v_add_f32_e32 v13, v221, v113
	v_cvt_pk_bf16_f32 v218, v12, v12
	v_cvt_pk_bf16_f32 v219, v13, v13
	global_store_short v[216:217], v218, off offset:1536
	global_store_short v[216:217], v219, off offset:1664
	v_mul_f32_e32 v220, v1, v13
	v_mul_f32_e32 v221, v1, v12
	v_fma_f32 v220, v0, v12, -v220
	v_fma_f32 v221, v0, v13, v221
	v_add_f32_e32 v12, v220, v114
	v_add_f32_e32 v13, v221, v115
	v_cvt_pk_bf16_f32 v222, v12, v12
	v_cvt_pk_bf16_f32 v223, v13, v13
	global_store_short v[216:217], v222, off offset:2304
	global_store_short v[216:217], v223, off offset:2432
	v_mul_f32_e32 v220, v1, v13
	v_mul_f32_e32 v221, v1, v12
	v_fma_f32 v220, v0, v12, -v220
	v_fma_f32 v221, v0, v13, v221
	v_add_f32_e32 v12, v220, v116
	v_add_f32_e32 v13, v221, v117
	v_add_co_u32_e32 v216, vcc, 0xc00, v216
	s_nop 1
	v_addc_co_u32_e32 v217, vcc, 0, v217, vcc
	v_cvt_pk_bf16_f32 v218, v12, v12
	v_cvt_pk_bf16_f32 v219, v13, v13
	global_store_short v[216:217], v218, off
	global_store_short v[216:217], v219, off offset:128
	v_mul_f32_e32 v220, v1, v13
	v_mul_f32_e32 v221, v1, v12
	v_fma_f32 v220, v0, v12, -v220
	v_fma_f32 v221, v0, v13, v221
	v_add_f32_e32 v12, v220, v118
	v_add_f32_e32 v13, v221, v119
	v_cvt_pk_bf16_f32 v222, v12, v12
	v_cvt_pk_bf16_f32 v223, v13, v13
	global_store_short v[216:217], v222, off offset:768
	global_store_short v[216:217], v223, off offset:896
	v_mul_f32_e32 v220, v1, v13
	v_mul_f32_e32 v221, v1, v12
	v_fma_f32 v220, v0, v12, -v220
	v_fma_f32 v221, v0, v13, v221
	v_add_f32_e32 v12, v220, v120
	v_add_f32_e32 v13, v221, v121
	v_cvt_pk_bf16_f32 v218, v12, v12
	v_cvt_pk_bf16_f32 v219, v13, v13
	global_store_short v[216:217], v218, off offset:1536
	global_store_short v[216:217], v219, off offset:1664
	v_mul_f32_e32 v220, v1, v13
	v_mul_f32_e32 v221, v1, v12
	v_fma_f32 v220, v0, v12, -v220
	v_fma_f32 v221, v0, v13, v221
	v_add_f32_e32 v12, v220, v122
	v_add_f32_e32 v13, v221, v123
	v_cvt_pk_bf16_f32 v222, v12, v12
	v_cvt_pk_bf16_f32 v223, v13, v13
	global_store_short v[216:217], v222, off offset:2304
	global_store_short v[216:217], v223, off offset:2432
	v_mul_f32_e32 v220, v1, v13
	v_mul_f32_e32 v221, v1, v12
	v_fma_f32 v220, v0, v12, -v220
	v_fma_f32 v221, v0, v13, v221
	v_add_f32_e32 v12, v220, v124
	v_add_f32_e32 v13, v221, v125
	v_add_co_u32_e32 v216, vcc, 0xc00, v216
	s_nop 1
	v_addc_co_u32_e32 v217, vcc, 0, v217, vcc
	v_cvt_pk_bf16_f32 v218, v12, v12
	v_cvt_pk_bf16_f32 v219, v13, v13
	global_store_short v[216:217], v218, off
	global_store_short v[216:217], v219, off offset:128
	v_mul_f32_e32 v220, v1, v13
	v_mul_f32_e32 v221, v1, v12
	v_fma_f32 v220, v0, v12, -v220
	v_fma_f32 v221, v0, v13, v221
	v_add_f32_e32 v12, v220, v130
	v_add_f32_e32 v13, v221, v131
	v_cvt_pk_bf16_f32 v222, v12, v12
	v_cvt_pk_bf16_f32 v223, v13, v13
	global_store_short v[216:217], v222, off offset:768
	global_store_short v[216:217], v223, off offset:896
	v_mul_f32_e32 v220, v1, v13
	v_mul_f32_e32 v221, v1, v12
	v_fma_f32 v220, v0, v12, -v220
	v_fma_f32 v221, v0, v13, v221
	v_add_f32_e32 v12, v220, v132
	v_add_f32_e32 v13, v221, v133
	v_cvt_pk_bf16_f32 v218, v12, v12
	v_cvt_pk_bf16_f32 v219, v13, v13
	global_store_short v[216:217], v218, off offset:1536
	global_store_short v[216:217], v219, off offset:1664
	v_mul_f32_e32 v220, v1, v13
	v_mul_f32_e32 v221, v1, v12
	v_fma_f32 v220, v0, v12, -v220
	v_fma_f32 v221, v0, v13, v221
	v_add_f32_e32 v12, v220, v134
	v_add_f32_e32 v13, v221, v135
	v_cvt_pk_bf16_f32 v222, v12, v12
	v_cvt_pk_bf16_f32 v223, v13, v13
	global_store_short v[216:217], v222, off offset:2304
	global_store_short v[216:217], v223, off offset:2432
	v_mul_f32_e32 v220, v1, v13
	v_mul_f32_e32 v221, v1, v12
	v_fma_f32 v220, v0, v12, -v220
	v_fma_f32 v221, v0, v13, v221
	v_add_f32_e32 v12, v220, v136
	v_add_f32_e32 v13, v221, v137
	v_add_co_u32_e32 v216, vcc, 0xc00, v216
	s_nop 1
	v_addc_co_u32_e32 v217, vcc, 0, v217, vcc
	v_cvt_pk_bf16_f32 v218, v12, v12
	v_cvt_pk_bf16_f32 v219, v13, v13
	global_store_short v[216:217], v218, off
	global_store_short v[216:217], v219, off offset:128
	v_mul_f32_e32 v220, v1, v13
	v_mul_f32_e32 v221, v1, v12
	v_fma_f32 v220, v0, v12, -v220
	v_fma_f32 v221, v0, v13, v221
	v_add_f32_e32 v12, v220, v138
	v_add_f32_e32 v13, v221, v139
	v_cvt_pk_bf16_f32 v222, v12, v12
	v_cvt_pk_bf16_f32 v223, v13, v13
	global_store_short v[216:217], v222, off offset:768
	global_store_short v[216:217], v223, off offset:896
	v_mul_f32_e32 v220, v1, v13
	v_mul_f32_e32 v221, v1, v12
	v_fma_f32 v220, v0, v12, -v220
	v_fma_f32 v221, v0, v13, v221
	v_add_f32_e32 v12, v220, v140
	v_add_f32_e32 v13, v221, v141
	v_cvt_pk_bf16_f32 v218, v12, v12
	v_cvt_pk_bf16_f32 v219, v13, v13
	global_store_short v[216:217], v218, off offset:1536
	global_store_short v[216:217], v219, off offset:1664
	v_mul_f32_e32 v220, v1, v13
	v_mul_f32_e32 v221, v1, v12
	v_fma_f32 v220, v0, v12, -v220
	v_fma_f32 v221, v0, v13, v221
	v_add_f32_e32 v12, v220, v142
	v_add_f32_e32 v13, v221, v143
	v_cvt_pk_bf16_f32 v222, v12, v12
	v_cvt_pk_bf16_f32 v223, v13, v13
	global_store_short v[216:217], v222, off offset:2304
	global_store_short v[216:217], v223, off offset:2432
	v_mul_f32_e32 v220, v1, v13
	v_mul_f32_e32 v221, v1, v12
	v_fma_f32 v220, v0, v12, -v220
	v_fma_f32 v221, v0, v13, v221
	v_add_f32_e32 v12, v220, v144
	v_add_f32_e32 v13, v221, v145
	v_add_co_u32_e32 v216, vcc, 0xc00, v216
	s_nop 1
	v_addc_co_u32_e32 v217, vcc, 0, v217, vcc
	v_cvt_pk_bf16_f32 v218, v12, v12
	v_cvt_pk_bf16_f32 v219, v13, v13
	global_store_short v[216:217], v218, off
	global_store_short v[216:217], v219, off offset:128
; __global__ void __launch_bounds__(512, 2) mega(Params p) {
;     ...
;             for (int c0 = 0; c0 < 64; c0 += 16) { float sr[16], si[16];
; #pragma unroll
;                 for (int k = 0; k < 16; ++k) { sr[k] = Sp[(size_t)(c0 + k) * 128]; si[k] = Sp[(size_t)(c0 + k) * 128 + 64]; }
; #pragma unroll
;                 for (int k = 0; k < 16; ++k) { const unsigned w = pk2(hr, hi); Hp[(size_t)(c0 + k) * 384] = (bf16_t)(w & 0xffffu); Hp[(size_t)(c0 + k) * 384 + 64] = (bf16_t)(w >> 16);
;                     const float n_r = c_r * hr - c_i * hi + sr[k], n_i = c_r * hi + c_i * hr + si[k]; hr = n_r; hi = n_i; } }
;             if (wave == 7) { float* o = p.out + O_S5P + (((size_t)b * 32 + g) * 64 + lane) * 2; o[0] = hr; o[1] = hi; }
	v_mul_f32_e32 v220, v1, v13
	v_mul_f32_e32 v221, v1, v12
	v_fma_f32 v220, v0, v12, -v220
	v_fma_f32 v221, v0, v13, v221
	v_add_f32_e32 v12, v220, v146
	v_add_f32_e32 v13, v221, v147
	v_cvt_pk_bf16_f32 v222, v12, v12
	v_cvt_pk_bf16_f32 v223, v13, v13
	global_store_short v[216:217], v222, off offset:768
	global_store_short v[216:217], v223, off offset:896
	v_mul_f32_e32 v220, v1, v13
	v_mul_f32_e32 v221, v1, v12
	v_fma_f32 v220, v0, v12, -v220
	v_fma_f32 v221, v0, v13, v221
	v_add_f32_e32 v12, v220, v148
	v_add_f32_e32 v13, v221, v149
	v_cvt_pk_bf16_f32 v218, v12, v12
	v_cvt_pk_bf16_f32 v219, v13, v13
	global_store_short v[216:217], v218, off offset:1536
	global_store_short v[216:217], v219, off offset:1664
	v_mul_f32_e32 v220, v1, v13
	v_mul_f32_e32 v221, v1, v12
	v_fma_f32 v220, v0, v12, -v220
	v_fma_f32 v221, v0, v13, v221
	v_add_f32_e32 v12, v220, v150
	v_add_f32_e32 v13, v221, v151
	v_cvt_pk_bf16_f32 v222, v12, v12
	v_cvt_pk_bf16_f32 v223, v13, v13
	global_store_short v[216:217], v222, off offset:2304
	global_store_short v[216:217], v223, off offset:2432
	v_mul_f32_e32 v220, v1, v13
	v_mul_f32_e32 v221, v1, v12
	v_fma_f32 v220, v0, v12, -v220
	v_fma_f32 v221, v0, v13, v221
	v_add_f32_e32 v12, v220, v152
	v_add_f32_e32 v13, v221, v153
	v_add_co_u32_e32 v216, vcc, 0xc00, v216
	s_nop 1
	v_addc_co_u32_e32 v217, vcc, 0, v217, vcc
	v_cvt_pk_bf16_f32 v218, v12, v12
	v_cvt_pk_bf16_f32 v219, v13, v13
	global_store_short v[216:217], v218, off
	global_store_short v[216:217], v219, off offset:128
	v_mul_f32_e32 v220, v1, v13
	v_mul_f32_e32 v221, v1, v12
	v_fma_f32 v220, v0, v12, -v220
	v_fma_f32 v221, v0, v13, v221
	v_add_f32_e32 v12, v220, v154
	v_add_f32_e32 v13, v221, v155
	v_cvt_pk_bf16_f32 v222, v12, v12
	v_cvt_pk_bf16_f32 v223, v13, v13
	global_store_short v[216:217], v222, off offset:768
	global_store_short v[216:217], v223, off offset:896
	v_mul_f32_e32 v220, v1, v13
	v_mul_f32_e32 v221, v1, v12
	v_fma_f32 v220, v0, v12, -v220
	v_fma_f32 v221, v0, v13, v221
	v_add_f32_e32 v12, v220, v156
	v_add_f32_e32 v13, v221, v157
	v_cvt_pk_bf16_f32 v218, v12, v12
	v_cvt_pk_bf16_f32 v219, v13, v13
	global_store_short v[216:217], v218, off offset:1536
	global_store_short v[216:217], v219, off offset:1664
	v_mul_f32_e32 v220, v1, v13
	v_mul_f32_e32 v221, v1, v12
	v_fma_f32 v220, v0, v12, -v220
	v_fma_f32 v221, v0, v13, v221
	v_add_f32_e32 v12, v220, v158
	v_add_f32_e32 v13, v221, v159
	v_cvt_pk_bf16_f32 v222, v12, v12
	v_cvt_pk_bf16_f32 v223, v13, v13
	global_store_short v[216:217], v222, off offset:2304
	global_store_short v[216:217], v223, off offset:2432
	v_mul_f32_e32 v220, v1, v13
	v_mul_f32_e32 v221, v1, v12
	v_fma_f32 v220, v0, v12, -v220
	v_fma_f32 v221, v0, v13, v221
	v_add_f32_e32 v12, v220, v160
	v_add_f32_e32 v13, v221, v161
	v_add_co_u32_e32 v216, vcc, 0xc00, v216
	s_nop 1
	v_addc_co_u32_e32 v217, vcc, 0, v217, vcc
	v_cvt_pk_bf16_f32 v218, v12, v12
	v_cvt_pk_bf16_f32 v219, v13, v13
	global_store_short v[216:217], v218, off
	global_store_short v[216:217], v219, off offset:128
	v_mul_f32_e32 v220, v1, v13
	v_mul_f32_e32 v221, v1, v12
	v_fma_f32 v220, v0, v12, -v220
	v_fma_f32 v221, v0, v13, v221
	v_add_f32_e32 v12, v220, v162
	v_add_f32_e32 v13, v221, v163
	v_cvt_pk_bf16_f32 v222, v12, v12
	v_cvt_pk_bf16_f32 v223, v13, v13
	global_store_short v[216:217], v222, off offset:768
	global_store_short v[216:217], v223, off offset:896
	v_mul_f32_e32 v220, v1, v13
	v_mul_f32_e32 v221, v1, v12
	v_fma_f32 v220, v0, v12, -v220
	v_fma_f32 v221, v0, v13, v221
	v_add_f32_e32 v12, v220, v164
	v_add_f32_e32 v13, v221, v165
	v_cvt_pk_bf16_f32 v218, v12, v12
	v_cvt_pk_bf16_f32 v219, v13, v13
	global_store_short v[216:217], v218, off offset:1536
	global_store_short v[216:217], v219, off offset:1664
	v_mul_f32_e32 v220, v1, v13
	v_mul_f32_e32 v221, v1, v12
	v_fma_f32 v220, v0, v12, -v220
; __global__ void __launch_bounds__(512, 2) mega(Params p) {
;     ...
;             for (int c0 = 0; c0 < 64; c0 += 16) { float sr[16], si[16];
; #pragma unroll
;                 for (int k = 0; k < 16; ++k) { sr[k] = Sp[(size_t)(c0 + k) * 128]; si[k] = Sp[(size_t)(c0 + k) * 128 + 64]; }
; #pragma unroll
;                 for (int k = 0; k < 16; ++k) { const unsigned w = pk2(hr, hi); Hp[(size_t)(c0 + k) * 384] = (bf16_t)(w & 0xffffu); Hp[(size_t)(c0 + k) * 384 + 64] = (bf16_t)(w >> 16);
;                     const float n_r = c_r * hr - c_i * hi + sr[k], n_i = c_r * hi + c_i * hr + si[k]; hr = n_r; hi = n_i; } }
;             if (wave == 7) { float* o = p.out + O_S5P + (((size_t)b * 32 + g) * 64 + lane) * 2; o[0] = hr; o[1] = hi; }
	v_fma_f32 v221, v0, v13, v221
	v_add_f32_e32 v12, v220, v166
	v_add_f32_e32 v13, v221, v167
	v_cvt_pk_bf16_f32 v222, v12, v12
	v_cvt_pk_bf16_f32 v223, v13, v13
	global_store_short v[216:217], v222, off offset:2304
	global_store_short v[216:217], v223, off offset:2432
	v_mul_f32_e32 v220, v1, v13
	v_mul_f32_e32 v221, v1, v12
	v_fma_f32 v220, v0, v12, -v220
	v_fma_f32 v221, v0, v13, v221
	v_add_f32_e32 v12, v220, v168
	v_add_f32_e32 v13, v221, v169
	v_add_co_u32_e32 v216, vcc, 0xc00, v216
	s_nop 1
	v_addc_co_u32_e32 v217, vcc, 0, v217, vcc
	v_cvt_pk_bf16_f32 v218, v12, v12
	v_cvt_pk_bf16_f32 v219, v13, v13
	global_store_short v[216:217], v218, off
	global_store_short v[216:217], v219, off offset:128
	v_mul_f32_e32 v220, v1, v13
	v_mul_f32_e32 v221, v1, v12
	v_fma_f32 v220, v0, v12, -v220
	v_fma_f32 v221, v0, v13, v221
	v_add_f32_e32 v12, v220, v170
	v_add_f32_e32 v13, v221, v171
	v_cvt_pk_bf16_f32 v222, v12, v12
	v_cvt_pk_bf16_f32 v223, v13, v13
	global_store_short v[216:217], v222, off offset:768
	global_store_short v[216:217], v223, off offset:896
	v_mul_f32_e32 v220, v1, v13
	v_mul_f32_e32 v221, v1, v12
	v_fma_f32 v220, v0, v12, -v220
	v_fma_f32 v221, v0, v13, v221
	v_add_f32_e32 v12, v220, v172
	v_add_f32_e32 v13, v221, v173
	v_cvt_pk_bf16_f32 v218, v12, v12
	v_cvt_pk_bf16_f32 v219, v13, v13
	global_store_short v[216:217], v218, off offset:1536
	global_store_short v[216:217], v219, off offset:1664
	v_mul_f32_e32 v220, v1, v13
	v_mul_f32_e32 v221, v1, v12
	v_fma_f32 v220, v0, v12, -v220
	v_fma_f32 v221, v0, v13, v221
	v_add_f32_e32 v12, v220, v174
	v_add_f32_e32 v13, v221, v175
	v_cvt_pk_bf16_f32 v222, v12, v12
	v_cvt_pk_bf16_f32 v223, v13, v13
	global_store_short v[216:217], v222, off offset:2304
	global_store_short v[216:217], v223, off offset:2432
	v_mul_f32_e32 v220, v1, v13
	v_mul_f32_e32 v221, v1, v12
	v_fma_f32 v220, v0, v12, -v220
	v_fma_f32 v221, v0, v13, v221
	v_add_f32_e32 v12, v220, v176
	v_add_f32_e32 v13, v221, v177
	v_add_co_u32_e32 v216, vcc, 0xc00, v216
	s_nop 1
	v_addc_co_u32_e32 v217, vcc, 0, v217, vcc
	v_cvt_pk_bf16_f32 v218, v12, v12
	v_cvt_pk_bf16_f32 v219, v13, v13
	global_store_short v[216:217], v218, off
	global_store_short v[216:217], v219, off offset:128
	v_mul_f32_e32 v220, v1, v13
	v_mul_f32_e32 v221, v1, v12
	v_fma_f32 v220, v0, v12, -v220
	v_fma_f32 v221, v0, v13, v221
	v_add_f32_e32 v12, v220, v178
	v_add_f32_e32 v13, v221, v179
	v_cvt_pk_bf16_f32 v222, v12, v12
	v_cvt_pk_bf16_f32 v223, v13, v13
	global_store_short v[216:217], v222, off offset:768
	global_store_short v[216:217], v223, off offset:896
	v_mul_f32_e32 v220, v1, v13
	v_mul_f32_e32 v221, v1, v12
	v_fma_f32 v220, v0, v12, -v220
	v_fma_f32 v221, v0, v13, v221
	v_add_f32_e32 v12, v220, v180
	v_add_f32_e32 v13, v221, v181
	v_cvt_pk_bf16_f32 v218, v12, v12
	v_cvt_pk_bf16_f32 v219, v13, v13
	global_store_short v[216:217], v218, off offset:1536
	global_store_short v[216:217], v219, off offset:1664
	v_mul_f32_e32 v220, v1, v13
	v_mul_f32_e32 v221, v1, v12
	v_fma_f32 v220, v0, v12, -v220
	v_fma_f32 v221, v0, v13, v221
	v_add_f32_e32 v12, v220, v182
	v_add_f32_e32 v13, v221, v183
	v_cvt_pk_bf16_f32 v222, v12, v12
	v_cvt_pk_bf16_f32 v223, v13, v13
	global_store_short v[216:217], v222, off offset:2304
	global_store_short v[216:217], v223, off offset:2432
	v_mul_f32_e32 v220, v1, v13
	v_mul_f32_e32 v221, v1, v12
	v_fma_f32 v220, v0, v12, -v220
	v_fma_f32 v221, v0, v13, v221
	v_add_f32_e32 v12, v220, v184
	v_add_f32_e32 v13, v221, v185
	s_cmp_eq_u32 s87, 7
	s_cbranch_scc0 .LBB0_686
	s_and_b32 s3, s84, 0x60
	s_or_b32 s3, s3, s10
	s_lshl_b32 s4, s3, 6
	s_mov_b32 s5, 0
	v_lshl_add_u64 v[0:1], v[128:129], 0, s[4:5]
	v_lshl_add_u64 v[0:1], v[0:1], 3, s[0:1]
	v_add_co_u32_e32 v0, vcc, 0x809e000, v0
	s_nop 1
	v_addc_co_u32_e32 v1, vcc, 0, v1, vcc
	global_store_dwordx2 v[0:1], v[12:13], off
